# GEMM epilogue stores of Hb, residual X and q/k/vT made write-through (sc1) so the grid barrier release finds less dirty L2
# speedup vs baseline: 1.0024x; 1.0024x over previous
; __device__ __forceinline__ unsigned cvt_pk_bf16(float lo, float hi) { unsigned r; asm volatile("v_cvt_pk_bf16_f32 %0, %1, %2" : "=v"(r) : "v"(lo), "v"(hi)); return r; }
;     __device__ __forceinline__ void operator()(const f32x4 (&acc)[2][2][4][2], const Unit& u, int wr, int wc, int fr, int fq) const {
;         const int row0 = u.pm * BM + wr * 64 + fr, col0 = u.pn * BM + wc * 32 + 8 * fq;
;         const float sc = (u.pn * BM < qcols) ? qscale : 1.0f;
; #pragma unroll
;         for (int ai = 0; ai < 2; ++ai)
; #pragma unroll
;             for (int m = 0; m < 4; ++m)
; #pragma unroll
;                 for (int bj = 0; bj < 2; ++bj) {
;                     const f32x4 v0 = acc[ai][bj][m][0] * sc, v1 = acc[ai][bj][m][1] * sc;
;                     u32x4e w; w.x = cvt_pk_bf16(v0[0], v0[1]); w.y = cvt_pk_bf16(v0[2], v0[3]); w.z = cvt_pk_bf16(v1[0], v1[1]); w.w = cvt_pk_bf16(v1[2], v1[3]);
;                     *(u32x4e*)(O + (size_t)(row0 + ai * HALF + m * 16) * ldc + col0 + bj * HALF) = w;
;                 }
.LBB0_697:
	s_lshl_b32 s19, s57, 8
	s_cmp_lt_i32 s19, s38
	s_cselect_b64 vcc, -1, 0
	v_cndmask_b32_e32 v140, 1.0, v234, vcc
	v_lshl_add_u32 v145, s26, 8, v141
	v_or_b32_e32 v146, s19, v143
	v_pk_mul_f32 v[128:129], v[140:141], v[128:129] op_sel_hi:[0,1]
	v_pk_mul_f32 v[124:125], v[140:141], v[124:125] op_sel_hi:[0,1]
	v_ashrrev_i32_e32 v147, 31, v146
	v_pk_mul_f32 v[130:131], v[140:141], v[130:131] op_sel_hi:[0,1]
	v_pk_mul_f32 v[148:149], v[140:141], v[126:127] op_sel_hi:[0,1]
	v_cvt_pk_bf16_f32 v126, v128, v129
	v_cvt_pk_bf16_f32 v127, v130, v131
	v_cvt_pk_bf16_f32 v128, v124, v125
	v_mad_i64_i32 v[124:125], s[28:29], s6, v145, 0
	v_lshl_add_u64 v[130:131], v[124:125], 1, s[8:9]
	v_lshlrev_b64 v[124:125], 1, v[146:147]
	v_lshl_add_u64 v[130:131], v[130:131], 0, v[124:125]
	v_cvt_pk_bf16_f32 v129, v148, v149
	global_store_dwordx4 v[130:131], v[126:129], off sc1
	v_pk_mul_f32 v[122:123], v[140:141], v[122:123] op_sel_hi:[0,1]
	v_pk_mul_f32 v[120:121], v[140:141], v[120:121] op_sel_hi:[0,1]
	v_pk_mul_f32 v[126:127], v[140:141], v[114:115] op_sel_hi:[0,1]
	v_pk_mul_f32 v[114:115], v[140:141], v[112:113] op_sel_hi:[0,1]
	v_cvt_pk_bf16_f32 v112, v120, v121
	v_cvt_pk_bf16_f32 v113, v122, v123
	v_cvt_pk_bf16_f32 v114, v114, v115
	v_cvt_pk_bf16_f32 v115, v126, v127
	global_store_dwordx4 v[130:131], v[112:115], off offset:256 sc1
	v_or_b32_e32 v120, 16, v145
	v_pk_mul_f32 v[106:107], v[140:141], v[106:107] op_sel_hi:[0,1]
	v_pk_mul_f32 v[112:113], v[140:141], v[118:119] op_sel_hi:[0,1]
	v_pk_mul_f32 v[114:115], v[140:141], v[116:117] op_sel_hi:[0,1]
	v_pk_mul_f32 v[116:117], v[140:141], v[110:111] op_sel_hi:[0,1]
	v_pk_mul_f32 v[110:111], v[140:141], v[108:109] op_sel_hi:[0,1]
	v_cvt_pk_bf16_f32 v108, v114, v115
	v_cvt_pk_bf16_f32 v109, v112, v113
	v_mad_i64_i32 v[112:113], s[28:29], s6, v120, 0
	v_lshl_add_u64 v[112:113], v[112:113], 1, s[8:9]
	v_lshl_add_u64 v[112:113], v[112:113], 0, v[124:125]
	v_cvt_pk_bf16_f32 v110, v110, v111
	v_cvt_pk_bf16_f32 v111, v116, v117
	global_store_dwordx4 v[112:113], v[108:111], off sc1
	v_pk_mul_f32 v[104:105], v[140:141], v[104:105] op_sel_hi:[0,1]
	v_pk_mul_f32 v[90:91], v[140:141], v[90:91] op_sel_hi:[0,1]
	v_pk_mul_f32 v[108:109], v[140:141], v[98:99] op_sel_hi:[0,1]
	v_pk_mul_f32 v[98:99], v[140:141], v[96:97] op_sel_hi:[0,1]
	v_cvt_pk_bf16_f32 v96, v104, v105
	v_cvt_pk_bf16_f32 v97, v106, v107
	v_cvt_pk_bf16_f32 v98, v98, v99
	v_cvt_pk_bf16_f32 v99, v108, v109
	global_store_dwordx4 v[112:113], v[96:99], off offset:256 sc1
	v_or_b32_e32 v104, 32, v145
	v_pk_mul_f32 v[88:89], v[140:141], v[88:89] op_sel_hi:[0,1]
	v_pk_mul_f32 v[96:97], v[140:141], v[102:103] op_sel_hi:[0,1]
	v_pk_mul_f32 v[98:99], v[140:141], v[100:101] op_sel_hi:[0,1]
	v_pk_mul_f32 v[100:101], v[140:141], v[94:95] op_sel_hi:[0,1]
	v_pk_mul_f32 v[94:95], v[140:141], v[92:93] op_sel_hi:[0,1]
	v_cvt_pk_bf16_f32 v92, v98, v99
	v_cvt_pk_bf16_f32 v93, v96, v97
	v_mad_i64_i32 v[96:97], s[28:29], s6, v104, 0
	v_lshl_add_u64 v[96:97], v[96:97], 1, s[8:9]
	v_lshl_add_u64 v[96:97], v[96:97], 0, v[124:125]
	v_cvt_pk_bf16_f32 v94, v94, v95
	v_cvt_pk_bf16_f32 v95, v100, v101
	global_store_dwordx4 v[96:97], v[92:95], off sc1
	v_pk_mul_f32 v[74:75], v[140:141], v[74:75] op_sel_hi:[0,1]
	v_pk_mul_f32 v[72:73], v[140:141], v[72:73] op_sel_hi:[0,1]
	v_pk_mul_f32 v[92:93], v[140:141], v[82:83] op_sel_hi:[0,1]
	v_pk_mul_f32 v[82:83], v[140:141], v[80:81] op_sel_hi:[0,1]
	v_cvt_pk_bf16_f32 v80, v88, v89
	v_cvt_pk_bf16_f32 v81, v90, v91
	v_cvt_pk_bf16_f32 v82, v82, v83
	v_cvt_pk_bf16_f32 v83, v92, v93
	global_store_dwordx4 v[96:97], v[80:83], off offset:256 sc1
	v_or_b32_e32 v88, 48, v145
	v_pk_mul_f32 v[64:65], v[140:141], v[64:65] op_sel_hi:[0,1]
	v_pk_mul_f32 v[80:81], v[140:141], v[86:87] op_sel_hi:[0,1]
	v_pk_mul_f32 v[82:83], v[140:141], v[84:85] op_sel_hi:[0,1]
	v_pk_mul_f32 v[84:85], v[140:141], v[78:79] op_sel_hi:[0,1]
	v_pk_mul_f32 v[78:79], v[140:141], v[76:77] op_sel_hi:[0,1]
	v_cvt_pk_bf16_f32 v76, v82, v83
	v_cvt_pk_bf16_f32 v77, v80, v81
	v_mad_i64_i32 v[80:81], s[28:29], s6, v88, 0
	v_lshl_add_u64 v[80:81], v[80:81], 1, s[8:9]
	v_lshl_add_u64 v[80:81], v[80:81], 0, v[124:125]
	v_cvt_pk_bf16_f32 v78, v78, v79
	v_cvt_pk_bf16_f32 v79, v84, v85
	global_store_dwordx4 v[80:81], v[76:79], off sc1
	v_pk_mul_f32 v[66:67], v[140:141], v[66:67] op_sel_hi:[0,1]
	v_pk_mul_f32 v[58:59], v[140:141], v[58:59] op_sel_hi:[0,1]
	v_pk_mul_f32 v[76:77], v[140:141], v[70:71] op_sel_hi:[0,1]
; __device__ __forceinline__ unsigned cvt_pk_bf16(float lo, float hi) { unsigned r; asm volatile("v_cvt_pk_bf16_f32 %0, %1, %2" : "=v"(r) : "v"(lo), "v"(hi)); return r; }
; #define PG8_BAR __builtin_amdgcn_s_barrier()
; template <class Epi, class Sched, bool ALIGN_EPI = false, bool SP2 = false>
; __device__ __forceinline__ void gemm_phase(PG8_LAS unsigned char* lds, const Gemm g, const Sched& S, const Epi& E) {
;     ...
;         if constexpr (ALIGN_EPI) { if (wr == 0) PG8_BAR; }
;         if constexpr (!Epi::AFTER_DRAIN) { E(acc, cur, wr, wc, fr, fq); S.done(cur); }
;         if (!has_next) break;
; #pragma unroll
;         for (int a = 0; a < 2; ++a)
; #pragma unroll
;             for (int b = 0; b < 2; ++b)
; #pragma unroll
;                 for (int m = 0; m < 4; ++m)
; #pragma unroll
;                     for (int n = 0; n < 2; ++n) acc[a][b][m][n] = (f32x4){0.f, 0.f, 0.f, 0.f};
;         cur = nxt; cA = nA; cB = nB; ++ui;
;         if constexpr (ALIGN_EPI) { if (wr == 1) PG8_BAR; }
;     __device__ __forceinline__ void operator()(const f32x4 (&acc)[2][2][4][2], const Unit& u, int wr, int wc, int fr, int fq) const {
;     ...
;         for (int ai = 0; ai < 2; ++ai)
; #pragma unroll
;             for (int m = 0; m < 4; ++m)
; #pragma unroll
;                 for (int bj = 0; bj < 2; ++bj) {
;                     const f32x4 v0 = acc[ai][bj][m][0] * sc, v1 = acc[ai][bj][m][1] * sc;
;                     u32x4e w; w.x = cvt_pk_bf16(v0[0], v0[1]); w.y = cvt_pk_bf16(v0[2], v0[3]); w.z = cvt_pk_bf16(v1[0], v1[1]); w.w = cvt_pk_bf16(v1[2], v1[3]);
;                     *(u32x4e*)(O + (size_t)(row0 + ai * HALF + m * 16) * ldc + col0 + bj * HALF) = w;
;                 }
	v_pk_mul_f32 v[70:71], v[140:141], v[68:69] op_sel_hi:[0,1]
	v_cvt_pk_bf16_f32 v68, v72, v73
	v_cvt_pk_bf16_f32 v69, v74, v75
	v_cvt_pk_bf16_f32 v70, v70, v71
	v_cvt_pk_bf16_f32 v71, v76, v77
	global_store_dwordx4 v[80:81], v[68:71], off offset:256 sc1
	v_pk_mul_f32 v[56:57], v[140:141], v[56:57] op_sel_hi:[0,1]
	v_pk_mul_f32 v[42:43], v[140:141], v[42:43] op_sel_hi:[0,1]
	v_add_u32_e32 v70, 0x80, v145
	v_pk_mul_f32 v[68:69], v[140:141], v[62:63] op_sel_hi:[0,1]
	v_pk_mul_f32 v[62:63], v[140:141], v[60:61] op_sel_hi:[0,1]
	v_cvt_pk_bf16_f32 v60, v64, v65
	v_mad_i64_i32 v[64:65], s[28:29], s6, v70, 0
	v_lshl_add_u64 v[64:65], v[64:65], 1, s[8:9]
	v_cvt_pk_bf16_f32 v61, v66, v67
	v_lshl_add_u64 v[64:65], v[64:65], 0, v[124:125]
	v_cvt_pk_bf16_f32 v62, v62, v63
	v_cvt_pk_bf16_f32 v63, v68, v69
	global_store_dwordx4 v[64:65], v[60:63], off sc1
	v_pk_mul_f32 v[40:41], v[140:141], v[40:41] op_sel_hi:[0,1]
	v_pk_mul_f32 v[26:27], v[140:141], v[26:27] op_sel_hi:[0,1]
	v_pk_mul_f32 v[60:61], v[140:141], v[50:51] op_sel_hi:[0,1]
	v_pk_mul_f32 v[50:51], v[140:141], v[48:49] op_sel_hi:[0,1]
	v_cvt_pk_bf16_f32 v48, v56, v57
	v_cvt_pk_bf16_f32 v49, v58, v59
	v_cvt_pk_bf16_f32 v50, v50, v51
	v_cvt_pk_bf16_f32 v51, v60, v61
	global_store_dwordx4 v[64:65], v[48:51], off offset:256 sc1
	v_add_u32_e32 v56, 0x90, v145
	v_pk_mul_f32 v[24:25], v[140:141], v[24:25] op_sel_hi:[0,1]
	v_pk_mul_f32 v[48:49], v[140:141], v[54:55] op_sel_hi:[0,1]
	v_pk_mul_f32 v[50:51], v[140:141], v[52:53] op_sel_hi:[0,1]
	v_pk_mul_f32 v[52:53], v[140:141], v[46:47] op_sel_hi:[0,1]
	v_pk_mul_f32 v[46:47], v[140:141], v[44:45] op_sel_hi:[0,1]
	v_cvt_pk_bf16_f32 v44, v50, v51
	v_cvt_pk_bf16_f32 v45, v48, v49
	v_mad_i64_i32 v[48:49], s[28:29], s6, v56, 0
	v_lshl_add_u64 v[48:49], v[48:49], 1, s[8:9]
	v_lshl_add_u64 v[48:49], v[48:49], 0, v[124:125]
	v_cvt_pk_bf16_f32 v46, v46, v47
	v_cvt_pk_bf16_f32 v47, v52, v53
	global_store_dwordx4 v[48:49], v[44:47], off sc1
	s_andn2_b64 vcc, exec, s[0:1]
	s_mov_b64 s[0:1], -1
	v_pk_mul_f32 v[44:45], v[140:141], v[34:35] op_sel_hi:[0,1]
	v_pk_mul_f32 v[34:35], v[140:141], v[32:33] op_sel_hi:[0,1]
	v_cvt_pk_bf16_f32 v32, v40, v41
	v_cvt_pk_bf16_f32 v33, v42, v43
	v_cvt_pk_bf16_f32 v34, v34, v35
	v_cvt_pk_bf16_f32 v35, v44, v45
	global_store_dwordx4 v[48:49], v[32:35], off offset:256 sc1
	v_add_u32_e32 v40, 0xa0, v145
	v_pk_mul_f32 v[10:11], v[140:141], v[10:11] op_sel_hi:[0,1]
	v_pk_mul_f32 v[32:33], v[140:141], v[38:39] op_sel_hi:[0,1]
	v_pk_mul_f32 v[34:35], v[140:141], v[36:37] op_sel_hi:[0,1]
	v_pk_mul_f32 v[36:37], v[140:141], v[30:31] op_sel_hi:[0,1]
	v_pk_mul_f32 v[30:31], v[140:141], v[28:29] op_sel_hi:[0,1]
	v_cvt_pk_bf16_f32 v28, v34, v35
	v_cvt_pk_bf16_f32 v29, v32, v33
	v_mad_i64_i32 v[32:33], s[28:29], s6, v40, 0
	v_lshl_add_u64 v[32:33], v[32:33], 1, s[8:9]
	v_lshl_add_u64 v[32:33], v[32:33], 0, v[124:125]
	v_cvt_pk_bf16_f32 v30, v30, v31
	v_cvt_pk_bf16_f32 v31, v36, v37
	global_store_dwordx4 v[32:33], v[28:31], off sc1
	v_pk_mul_f32 v[8:9], v[140:141], v[8:9] op_sel_hi:[0,1]
	s_nop 0
	v_pk_mul_f32 v[28:29], v[140:141], v[18:19] op_sel_hi:[0,1]
	v_pk_mul_f32 v[18:19], v[140:141], v[16:17] op_sel_hi:[0,1]
	v_cvt_pk_bf16_f32 v16, v24, v25
	v_cvt_pk_bf16_f32 v17, v26, v27
	v_cvt_pk_bf16_f32 v18, v18, v19
	v_cvt_pk_bf16_f32 v19, v28, v29
	global_store_dwordx4 v[32:33], v[16:19], off offset:256 sc1
	v_add_u32_e32 v24, 0xb0, v145
	s_nop 0
	v_pk_mul_f32 v[16:17], v[140:141], v[22:23] op_sel_hi:[0,1]
	v_pk_mul_f32 v[18:19], v[140:141], v[20:21] op_sel_hi:[0,1]
	v_pk_mul_f32 v[20:21], v[140:141], v[14:15] op_sel_hi:[0,1]
	v_pk_mul_f32 v[14:15], v[140:141], v[12:13] op_sel_hi:[0,1]
	v_cvt_pk_bf16_f32 v12, v18, v19
	v_cvt_pk_bf16_f32 v13, v16, v17
	v_mad_i64_i32 v[16:17], s[28:29], s6, v24, 0
	v_lshl_add_u64 v[16:17], v[16:17], 1, s[8:9]
	v_lshl_add_u64 v[16:17], v[16:17], 0, v[124:125]
	v_cvt_pk_bf16_f32 v14, v14, v15
	v_cvt_pk_bf16_f32 v15, v20, v21
	global_store_dwordx4 v[16:17], v[12:15], off sc1
	s_nop 1
	v_pk_mul_f32 v[12:13], v[140:141], v[6:7] op_sel_hi:[0,1]
	v_pk_mul_f32 v[6:7], v[140:141], v[4:5] op_sel_hi:[0,1]
	v_cvt_pk_bf16_f32 v4, v8, v9
	v_cvt_pk_bf16_f32 v5, v10, v11
	v_cvt_pk_bf16_f32 v6, v6, v7
	v_cvt_pk_bf16_f32 v7, v12, v13
	global_store_dwordx4 v[16:17], v[4:7], off offset:256 sc1
	s_cbranch_vccnz .LBB0_686
	s_andn2_b64 vcc, exec, s[14:15]
	s_cbranch_vccnz .LBB0_685
	s_barrier
	s_branch .LBB0_685

;     __device__ __forceinline__ void fused(f32x4 (&acc)[2][2][4][2], const Unit& u, int wr, int wc, int fr, int fq, PG8_LAS unsigned char* lds, int wid, int lane) const {
;     ...
;                 for (int m = 0; m < 4; ++m) { const int r = ai * HALF + wr * 64 + m * 16 + fr; const size_t off = (size_t)(u.pm * BM + r) * 1024 + c;
;                     const f32x4 x0 = acc[ai][bj][m][0], x1 = acc[ai][bj][m][1];
;                     if (XF) { *(f32x4*)(XF + off) = x0; *(f32x4*)(XF + off + 4) = x1; }
;                     else { u32x4v w; w.x = cvt_pk_f16(x0[0], x0[1]); w.y = cvt_pk_f16(x0[2], x0[3]); w.z = cvt_pk_f16(x1[0], x1[1]); w.w = cvt_pk_f16(x1[2], x1[3]); *(u32x4v*)(X + off) = w; }
.LBB0_789:
	v_cvt_pk_f16_f32 v126, v96, v97
	v_cvt_pk_f16_f32 v127, v98, v99
	v_cvt_pk_f16_f32 v128, v160, v161
	v_cvt_pk_f16_f32 v129, v162, v163
	flat_store_dwordx4 v[122:123], v[126:129] sc1

;     __device__ __forceinline__ void fused(f32x4 (&acc)[2][2][4][2], const Unit& u, int wr, int wc, int fr, int fq, PG8_LAS unsigned char* lds, int wid, int lane) const {
;     ...
;                 for (int m = 0; m < 4; ++m) { const int r = ai * HALF + wr * 64 + m * 16 + fr; const size_t off = (size_t)(u.pm * BM + r) * 1024 + c;
;                     const f32x4 x0 = acc[ai][bj][m][0], x1 = acc[ai][bj][m][1];
;                     if (XF) { *(f32x4*)(XF + off) = x0; *(f32x4*)(XF + off + 4) = x1; }
;                     else { u32x4v w; w.x = cvt_pk_f16(x0[0], x0[1]); w.y = cvt_pk_f16(x0[2], x0[3]); w.z = cvt_pk_f16(x1[0], x1[1]); w.w = cvt_pk_f16(x1[2], x1[3]); *(u32x4v*)(X + off) = w; }
.LBB0_794:
	v_cvt_pk_f16_f32 v128, v88, v89
	v_cvt_pk_f16_f32 v129, v90, v91
	v_cvt_pk_f16_f32 v130, v156, v157
	v_cvt_pk_f16_f32 v131, v158, v159
	flat_store_dwordx4 v[98:99], v[128:131] sc1

;     __device__ __forceinline__ void fused(f32x4 (&acc)[2][2][4][2], const Unit& u, int wr, int wc, int fr, int fq, PG8_LAS unsigned char* lds, int wid, int lane) const {
;     ...
;                 for (int m = 0; m < 4; ++m) { const int r = ai * HALF + wr * 64 + m * 16 + fr; const size_t off = (size_t)(u.pm * BM + r) * 1024 + c;
;                     const f32x4 x0 = acc[ai][bj][m][0], x1 = acc[ai][bj][m][1];
;                     if (XF) { *(f32x4*)(XF + off) = x0; *(f32x4*)(XF + off + 4) = x1; }
;                     else { u32x4v w; w.x = cvt_pk_f16(x0[0], x0[1]); w.y = cvt_pk_f16(x0[2], x0[3]); w.z = cvt_pk_f16(x1[0], x1[1]); w.w = cvt_pk_f16(x1[2], x1[3]); *(u32x4v*)(X + off) = w; }
.LBB0_799:
	v_cvt_pk_f16_f32 v132, v92, v93
	v_cvt_pk_f16_f32 v133, v94, v95
	v_cvt_pk_f16_f32 v134, v152, v153
	v_cvt_pk_f16_f32 v135, v154, v155
	flat_store_dwordx4 v[128:129], v[132:135] sc1

;     __device__ __forceinline__ void fused(f32x4 (&acc)[2][2][4][2], const Unit& u, int wr, int wc, int fr, int fq, PG8_LAS unsigned char* lds, int wid, int lane) const {
;     ...
;                 for (int m = 0; m < 4; ++m) { const int r = ai * HALF + wr * 64 + m * 16 + fr; const size_t off = (size_t)(u.pm * BM + r) * 1024 + c;
;                     const f32x4 x0 = acc[ai][bj][m][0], x1 = acc[ai][bj][m][1];
;                     if (XF) { *(f32x4*)(XF + off) = x0; *(f32x4*)(XF + off + 4) = x1; }
;                     else { u32x4v w; w.x = cvt_pk_f16(x0[0], x0[1]); w.y = cvt_pk_f16(x0[2], x0[3]); w.z = cvt_pk_f16(x1[0], x1[1]); w.w = cvt_pk_f16(x1[2], x1[3]); *(u32x4v*)(X + off) = w; }
.LBB0_804:
	v_cvt_pk_f16_f32 v132, v72, v73
	v_cvt_pk_f16_f32 v133, v74, v75
	v_cvt_pk_f16_f32 v134, v148, v149
	v_cvt_pk_f16_f32 v135, v150, v151
	flat_store_dwordx4 v[92:93], v[132:135] sc1

;     __device__ __forceinline__ void fused(f32x4 (&acc)[2][2][4][2], const Unit& u, int wr, int wc, int fr, int fq, PG8_LAS unsigned char* lds, int wid, int lane) const {
;     ...
;                 for (int m = 0; m < 4; ++m) { const int r = ai * HALF + wr * 64 + m * 16 + fr; const size_t off = (size_t)(u.pm * BM + r) * 1024 + c;
;                     const f32x4 x0 = acc[ai][bj][m][0], x1 = acc[ai][bj][m][1];
;                     if (XF) { *(f32x4*)(XF + off) = x0; *(f32x4*)(XF + off + 4) = x1; }
;                     else { u32x4v w; w.x = cvt_pk_f16(x0[0], x0[1]); w.y = cvt_pk_f16(x0[2], x0[3]); w.z = cvt_pk_f16(x1[0], x1[1]); w.w = cvt_pk_f16(x1[2], x1[3]); *(u32x4v*)(X + off) = w; }
.LBB0_809:
	v_cvt_pk_f16_f32 v148, v80, v81
	v_cvt_pk_f16_f32 v149, v82, v83
	v_cvt_pk_f16_f32 v150, v144, v145
	v_cvt_pk_f16_f32 v151, v146, v147
	flat_store_dwordx4 v[132:133], v[148:151] sc1

;     __device__ __forceinline__ void fused(f32x4 (&acc)[2][2][4][2], const Unit& u, int wr, int wc, int fr, int fq, PG8_LAS unsigned char* lds, int wid, int lane) const {
;     ...
;                 for (int m = 0; m < 4; ++m) { const int r = ai * HALF + wr * 64 + m * 16 + fr; const size_t off = (size_t)(u.pm * BM + r) * 1024 + c;
;                     const f32x4 x0 = acc[ai][bj][m][0], x1 = acc[ai][bj][m][1];
;                     if (XF) { *(f32x4*)(XF + off) = x0; *(f32x4*)(XF + off + 4) = x1; }
;                     else { u32x4v w; w.x = cvt_pk_f16(x0[0], x0[1]); w.y = cvt_pk_f16(x0[2], x0[3]); w.z = cvt_pk_f16(x1[0], x1[1]); w.w = cvt_pk_f16(x1[2], x1[3]); *(u32x4v*)(X + off) = w; }
.LBB0_814:
	v_cvt_pk_f16_f32 v144, v64, v65
	v_cvt_pk_f16_f32 v145, v66, v67
	v_cvt_pk_f16_f32 v146, v136, v137
	v_cvt_pk_f16_f32 v147, v138, v139
	flat_store_dwordx4 v[82:83], v[144:147] sc1

;     __device__ __forceinline__ void fused(f32x4 (&acc)[2][2][4][2], const Unit& u, int wr, int wc, int fr, int fq, PG8_LAS unsigned char* lds, int wid, int lane) const {
;     ...
;                 for (int m = 0; m < 4; ++m) { const int r = ai * HALF + wr * 64 + m * 16 + fr; const size_t off = (size_t)(u.pm * BM + r) * 1024 + c;
;                     const f32x4 x0 = acc[ai][bj][m][0], x1 = acc[ai][bj][m][1];
;                     if (XF) { *(f32x4*)(XF + off) = x0; *(f32x4*)(XF + off + 4) = x1; }
;                     else { u32x4v w; w.x = cvt_pk_f16(x0[0], x0[1]); w.y = cvt_pk_f16(x0[2], x0[3]); w.z = cvt_pk_f16(x1[0], x1[1]); w.w = cvt_pk_f16(x1[2], x1[3]); *(u32x4v*)(X + off) = w; }
.LBB0_819:
	v_cvt_pk_f16_f32 v144, v68, v69
	v_cvt_pk_f16_f32 v145, v70, v71
	v_cvt_pk_f16_f32 v146, v116, v117
	v_cvt_pk_f16_f32 v147, v118, v119
	flat_store_dwordx4 v[136:137], v[144:147] sc1

;     __device__ __forceinline__ void fused(f32x4 (&acc)[2][2][4][2], const Unit& u, int wr, int wc, int fr, int fq, PG8_LAS unsigned char* lds, int wid, int lane) const {
;     ...
;                 for (int m = 0; m < 4; ++m) { const int r = ai * HALF + wr * 64 + m * 16 + fr; const size_t off = (size_t)(u.pm * BM + r) * 1024 + c;
;                     const f32x4 x0 = acc[ai][bj][m][0], x1 = acc[ai][bj][m][1];
;                     if (XF) { *(f32x4*)(XF + off) = x0; *(f32x4*)(XF + off + 4) = x1; }
;                     else { u32x4v w; w.x = cvt_pk_f16(x0[0], x0[1]); w.y = cvt_pk_f16(x0[2], x0[3]); w.z = cvt_pk_f16(x1[0], x1[1]); w.w = cvt_pk_f16(x1[2], x1[3]); *(u32x4v*)(X + off) = w; }
.LBB0_824:
	v_cvt_pk_f16_f32 v66, v52, v53
	v_cvt_pk_f16_f32 v67, v54, v55
	v_cvt_pk_f16_f32 v68, v112, v113
	v_cvt_pk_f16_f32 v69, v114, v115
	flat_store_dwordx4 v[70:71], v[66:69] sc1

;     __device__ __forceinline__ void fused(f32x4 (&acc)[2][2][4][2], const Unit& u, int wr, int wc, int fr, int fq, PG8_LAS unsigned char* lds, int wid, int lane) const {
;     ...
;                 for (int m = 0; m < 4; ++m) { const int r = ai * HALF + wr * 64 + m * 16 + fr; const size_t off = (size_t)(u.pm * BM + r) * 1024 + c;
;                     const f32x4 x0 = acc[ai][bj][m][0], x1 = acc[ai][bj][m][1];
;                     if (XF) { *(f32x4*)(XF + off) = x0; *(f32x4*)(XF + off + 4) = x1; }
;                     else { u32x4v w; w.x = cvt_pk_f16(x0[0], x0[1]); w.y = cvt_pk_f16(x0[2], x0[3]); w.z = cvt_pk_f16(x1[0], x1[1]); w.w = cvt_pk_f16(x1[2], x1[3]); *(u32x4v*)(X + off) = w; }
.LBB0_833:
	v_cvt_pk_f16_f32 v106, v84, v85
	v_cvt_pk_f16_f32 v107, v86, v87
	v_cvt_pk_f16_f32 v108, v32, v33
	v_cvt_pk_f16_f32 v109, v34, v35
	flat_store_dwordx4 v[122:123], v[106:109] offset:256 sc1

;     __device__ __forceinline__ void fused(f32x4 (&acc)[2][2][4][2], const Unit& u, int wr, int wc, int fr, int fq, PG8_LAS unsigned char* lds, int wid, int lane) const {
;     ...
;                 for (int m = 0; m < 4; ++m) { const int r = ai * HALF + wr * 64 + m * 16 + fr; const size_t off = (size_t)(u.pm * BM + r) * 1024 + c;
;                     const f32x4 x0 = acc[ai][bj][m][0], x1 = acc[ai][bj][m][1];
;                     if (XF) { *(f32x4*)(XF + off) = x0; *(f32x4*)(XF + off + 4) = x1; }
;                     else { u32x4v w; w.x = cvt_pk_f16(x0[0], x0[1]); w.y = cvt_pk_f16(x0[2], x0[3]); w.z = cvt_pk_f16(x1[0], x1[1]); w.w = cvt_pk_f16(x1[2], x1[3]); *(u32x4v*)(X + off) = w; }
.LBB0_838:
	v_cvt_pk_f16_f32 v32, v76, v77
	v_cvt_pk_f16_f32 v33, v78, v79
	v_cvt_pk_f16_f32 v34, v28, v29
	v_cvt_pk_f16_f32 v35, v30, v31
	flat_store_dwordx4 v[98:99], v[32:35] offset:256 sc1

;     __device__ __forceinline__ void fused(f32x4 (&acc)[2][2][4][2], const Unit& u, int wr, int wc, int fr, int fq, PG8_LAS unsigned char* lds, int wid, int lane) const {
;     ...
;                 for (int m = 0; m < 4; ++m) { const int r = ai * HALF + wr * 64 + m * 16 + fr; const size_t off = (size_t)(u.pm * BM + r) * 1024 + c;
;                     const f32x4 x0 = acc[ai][bj][m][0], x1 = acc[ai][bj][m][1];
;                     if (XF) { *(f32x4*)(XF + off) = x0; *(f32x4*)(XF + off + 4) = x1; }
;                     else { u32x4v w; w.x = cvt_pk_f16(x0[0], x0[1]); w.y = cvt_pk_f16(x0[2], x0[3]); w.z = cvt_pk_f16(x1[0], x1[1]); w.w = cvt_pk_f16(x1[2], x1[3]); *(u32x4v*)(X + off) = w; }
.LBB0_843:
	v_cvt_pk_f16_f32 v28, v60, v61
	v_cvt_pk_f16_f32 v29, v62, v63
	v_cvt_pk_f16_f32 v30, v24, v25
	v_cvt_pk_f16_f32 v31, v26, v27
	flat_store_dwordx4 v[128:129], v[28:31] offset:256 sc1

;     __device__ __forceinline__ void fused(f32x4 (&acc)[2][2][4][2], const Unit& u, int wr, int wc, int fr, int fq, PG8_LAS unsigned char* lds, int wid, int lane) const {
;     ...
;                 for (int m = 0; m < 4; ++m) { const int r = ai * HALF + wr * 64 + m * 16 + fr; const size_t off = (size_t)(u.pm * BM + r) * 1024 + c;
;                     const f32x4 x0 = acc[ai][bj][m][0], x1 = acc[ai][bj][m][1];
;                     if (XF) { *(f32x4*)(XF + off) = x0; *(f32x4*)(XF + off + 4) = x1; }
;                     else { u32x4v w; w.x = cvt_pk_f16(x0[0], x0[1]); w.y = cvt_pk_f16(x0[2], x0[3]); w.z = cvt_pk_f16(x1[0], x1[1]); w.w = cvt_pk_f16(x1[2], x1[3]); *(u32x4v*)(X + off) = w; }
.LBB0_848:
	v_cvt_pk_f16_f32 v24, v56, v57
	v_cvt_pk_f16_f32 v25, v58, v59
	v_cvt_pk_f16_f32 v26, v20, v21
	v_cvt_pk_f16_f32 v27, v22, v23
	flat_store_dwordx4 v[92:93], v[24:27] offset:256 sc1

;     __device__ __forceinline__ void fused(f32x4 (&acc)[2][2][4][2], const Unit& u, int wr, int wc, int fr, int fq, PG8_LAS unsigned char* lds, int wid, int lane) const {
;     ...
;                 for (int m = 0; m < 4; ++m) { const int r = ai * HALF + wr * 64 + m * 16 + fr; const size_t off = (size_t)(u.pm * BM + r) * 1024 + c;
;                     const f32x4 x0 = acc[ai][bj][m][0], x1 = acc[ai][bj][m][1];
;                     if (XF) { *(f32x4*)(XF + off) = x0; *(f32x4*)(XF + off + 4) = x1; }
;                     else { u32x4v w; w.x = cvt_pk_f16(x0[0], x0[1]); w.y = cvt_pk_f16(x0[2], x0[3]); w.z = cvt_pk_f16(x1[0], x1[1]); w.w = cvt_pk_f16(x1[2], x1[3]); *(u32x4v*)(X + off) = w; }
.LBB0_853:
	v_cvt_pk_f16_f32 v20, v48, v49
	v_cvt_pk_f16_f32 v21, v50, v51
	v_cvt_pk_f16_f32 v22, v16, v17
	v_cvt_pk_f16_f32 v23, v18, v19
	flat_store_dwordx4 v[132:133], v[20:23] offset:256 sc1

;     __device__ __forceinline__ void fused(f32x4 (&acc)[2][2][4][2], const Unit& u, int wr, int wc, int fr, int fq, PG8_LAS unsigned char* lds, int wid, int lane) const {
;     ...
;                 for (int m = 0; m < 4; ++m) { const int r = ai * HALF + wr * 64 + m * 16 + fr; const size_t off = (size_t)(u.pm * BM + r) * 1024 + c;
;                     const f32x4 x0 = acc[ai][bj][m][0], x1 = acc[ai][bj][m][1];
;                     if (XF) { *(f32x4*)(XF + off) = x0; *(f32x4*)(XF + off + 4) = x1; }
;                     else { u32x4v w; w.x = cvt_pk_f16(x0[0], x0[1]); w.y = cvt_pk_f16(x0[2], x0[3]); w.z = cvt_pk_f16(x1[0], x1[1]); w.w = cvt_pk_f16(x1[2], x1[3]); *(u32x4v*)(X + off) = w; }
.LBB0_858:
	v_cvt_pk_f16_f32 v16, v44, v45
	v_cvt_pk_f16_f32 v17, v46, v47
	v_cvt_pk_f16_f32 v18, v12, v13
	v_cvt_pk_f16_f32 v19, v14, v15
	flat_store_dwordx4 v[82:83], v[16:19] offset:256 sc1

;     __device__ __forceinline__ void fused(f32x4 (&acc)[2][2][4][2], const Unit& u, int wr, int wc, int fr, int fq, PG8_LAS unsigned char* lds, int wid, int lane) const {
;     ...
;                 for (int m = 0; m < 4; ++m) { const int r = ai * HALF + wr * 64 + m * 16 + fr; const size_t off = (size_t)(u.pm * BM + r) * 1024 + c;
;                     const f32x4 x0 = acc[ai][bj][m][0], x1 = acc[ai][bj][m][1];
;                     if (XF) { *(f32x4*)(XF + off) = x0; *(f32x4*)(XF + off + 4) = x1; }
;                     else { u32x4v w; w.x = cvt_pk_f16(x0[0], x0[1]); w.y = cvt_pk_f16(x0[2], x0[3]); w.z = cvt_pk_f16(x1[0], x1[1]); w.w = cvt_pk_f16(x1[2], x1[3]); *(u32x4v*)(X + off) = w; }
.LBB0_863:
	v_cvt_pk_f16_f32 v12, v40, v41
	v_cvt_pk_f16_f32 v13, v42, v43
	v_cvt_pk_f16_f32 v14, v8, v9
	v_cvt_pk_f16_f32 v15, v10, v11
	flat_store_dwordx4 v[136:137], v[12:15] offset:256 sc1

;     __device__ __forceinline__ void fused(f32x4 (&acc)[2][2][4][2], const Unit& u, int wr, int wc, int fr, int fq, PG8_LAS unsigned char* lds, int wid, int lane) const {
;     ...
;                 for (int m = 0; m < 4; ++m) { const int r = ai * HALF + wr * 64 + m * 16 + fr; const size_t off = (size_t)(u.pm * BM + r) * 1024 + c;
;                     const f32x4 x0 = acc[ai][bj][m][0], x1 = acc[ai][bj][m][1];
;                     if (XF) { *(f32x4*)(XF + off) = x0; *(f32x4*)(XF + off + 4) = x1; }
;                     else { u32x4v w; w.x = cvt_pk_f16(x0[0], x0[1]); w.y = cvt_pk_f16(x0[2], x0[3]); w.z = cvt_pk_f16(x1[0], x1[1]); w.w = cvt_pk_f16(x1[2], x1[3]); *(u32x4v*)(X + off) = w; }
.LBB0_868:
	v_cvt_pk_f16_f32 v8, v36, v37
	v_cvt_pk_f16_f32 v9, v38, v39
	v_cvt_pk_f16_f32 v10, v4, v5
	v_cvt_pk_f16_f32 v11, v6, v7
	flat_store_dwordx4 v[70:71], v[8:11] offset:256 sc1

; __device__ __forceinline__ unsigned cvt_pk_bf16(float lo, float hi) { unsigned r; asm volatile("v_cvt_pk_bf16_f32 %0, %1, %2" : "=v"(r) : "v"(lo), "v"(hi)); return r; }
;     __device__ __forceinline__ void operator()(const f32x4 (&acc)[2][2][4][2], const Unit& u, int wr, int wc, int fr, int fq) const {
;         const int row0 = u.pm * BM + wr * 64 + fr, col0 = u.pn * HALF + wc * 32 + 8 * fq;
; #pragma unroll
;         for (int ai = 0; ai < 2; ++ai)
; #pragma unroll
;             for (int m = 0; m < 4; ++m) {
;                 float g8[8], u8[8], v[8];
; #pragma unroll
;                 for (int n = 0; n < 2; ++n)
; #pragma unroll
;                     for (int j = 0; j < 4; ++j) { g8[4 * n + j] = acc[ai][0][m][n][j]; u8[4 * n + j] = acc[ai][1][m][n][j]; }
; #pragma unroll
;                 for (int e = 0; e < 8; ++e) v[e] = __builtin_amdgcn_exp2f(-1.4426950408889634f * g8[e]);
; #pragma unroll
;                 for (int e = 0; e < 8; ++e) v[e] = __builtin_amdgcn_rcpf(1.0f + v[e]);
; #pragma unroll
;                 for (int e = 0; e < 8; ++e) v[e] = (g8[e] * u8[e]) * v[e];
;                 u32x4e w; w.x = cvt_pk_bf16(v[0], v[1]); w.y = cvt_pk_bf16(v[2], v[3]); w.z = cvt_pk_bf16(v[4], v[5]); w.w = cvt_pk_bf16(v[6], v[7]);
;                 *(u32x4e*)(H + (size_t)(row0 + ai * HALF + m * 16) * ldc + col0) = w;
;             }
.LBB0_886:
	v_mul_f32_e32 v147, 0xbfb8aa3b, v128
	v_mul_f32_e32 v148, 0xbfb8aa3b, v129
	v_mul_f32_e32 v149, 0xbfb8aa3b, v130
	v_mul_f32_e32 v151, 0xbfb8aa3b, v124
	v_mul_f32_e32 v152, 0xbfb8aa3b, v125
	v_exp_f32_e32 v147, v147
	v_exp_f32_e32 v148, v148
	v_exp_f32_e32 v149, v149
	v_mul_f32_e32 v150, 0xbfb8aa3b, v131
	v_exp_f32_e32 v151, v151
	v_exp_f32_e32 v152, v152
	v_mul_f32_e32 v153, 0xbfb8aa3b, v126
	v_mul_f32_e32 v154, 0xbfb8aa3b, v127
	v_exp_f32_e32 v150, v150
	v_exp_f32_e32 v153, v153
	v_exp_f32_e32 v154, v154
	v_add_f32_e32 v147, 1.0, v147
	v_add_f32_e32 v148, 1.0, v148
	v_add_f32_e32 v149, 1.0, v149
	v_add_f32_e32 v151, 1.0, v151
	v_add_f32_e32 v152, 1.0, v152
	v_rcp_f32_e32 v147, v147
	v_rcp_f32_e32 v148, v148
	v_rcp_f32_e32 v149, v149
	v_add_f32_e32 v150, 1.0, v150
	v_rcp_f32_e32 v151, v151
	v_rcp_f32_e32 v152, v152
	v_add_f32_e32 v153, 1.0, v153
	v_add_f32_e32 v154, 1.0, v154
	v_rcp_f32_e32 v150, v150
	v_rcp_f32_e32 v153, v153
	v_rcp_f32_e32 v154, v154
	v_mul_f32_e32 v120, v128, v120
	v_mul_f32_e32 v121, v129, v121
	v_mul_f32_e32 v122, v130, v122
	v_mul_f32_e32 v116, v124, v116
	v_mul_f32_e32 v117, v125, v117
	v_lshl_or_b32 v144, s30, 7, v142
	v_mul_f32_e32 v120, v147, v120
	v_mul_f32_e32 v121, v148, v121
	v_mul_f32_e32 v122, v149, v122
	v_mul_f32_e32 v123, v131, v123
	v_mul_f32_e32 v116, v151, v116
	v_mul_f32_e32 v117, v152, v117
	v_mul_f32_e32 v118, v126, v118
	v_mul_f32_e32 v119, v127, v119
	v_lshl_add_u32 v146, s31, 8, v140
	v_ashrrev_i32_e32 v145, 31, v144
	v_mul_f32_e32 v123, v150, v123
	v_mul_f32_e32 v118, v153, v118
	v_mul_f32_e32 v119, v154, v119
	v_cvt_pk_bf16_f32 v120, v120, v121
	v_cvt_pk_bf16_f32 v121, v122, v123
	v_cvt_pk_bf16_f32 v122, v116, v117
	v_mov_b64_e32 v[116:117], s[50:51]
	v_cvt_pk_bf16_f32 v123, v118, v119
	v_mad_i64_i32 v[124:125], s[16:17], v146, s44, v[116:117]
	v_lshlrev_b64 v[118:119], 1, v[144:145]
	v_lshl_add_u64 v[124:125], v[124:125], 0, v[118:119]
	global_store_dwordx4 v[124:125], v[120:123], off sc1
	v_mul_f32_e32 v124, 0xbfb8aa3b, v108
	v_exp_f32_e32 v124, v124
	v_mul_f32_e32 v125, 0xbfb8aa3b, v109
	v_mul_f32_e32 v120, 0xbfb8aa3b, v112
	v_exp_f32_e32 v125, v125
	v_mul_f32_e32 v126, 0xbfb8aa3b, v110
	v_exp_f32_e32 v120, v120
	v_mul_f32_e32 v121, 0xbfb8aa3b, v113
	v_exp_f32_e32 v126, v126
	v_mul_f32_e32 v127, 0xbfb8aa3b, v111
	v_exp_f32_e32 v121, v121
	v_exp_f32_e32 v127, v127
	v_add_f32_e32 v124, 1.0, v124
	v_mul_f32_e32 v122, 0xbfb8aa3b, v114
	v_mul_f32_e32 v123, 0xbfb8aa3b, v115
	v_rcp_f32_e32 v124, v124
	v_add_f32_e32 v125, 1.0, v125
	v_exp_f32_e32 v122, v122
	v_exp_f32_e32 v123, v123
	v_add_f32_e32 v120, 1.0, v120
	v_rcp_f32_e32 v125, v125
	v_add_f32_e32 v126, 1.0, v126
	v_rcp_f32_e32 v120, v120
	v_add_f32_e32 v121, 1.0, v121
	v_rcp_f32_e32 v126, v126
	v_add_f32_e32 v127, 1.0, v127
	v_rcp_f32_e32 v121, v121
	v_rcp_f32_e32 v127, v127
	v_mul_f32_e32 v100, v108, v100
	v_mul_f32_e32 v108, v124, v100
	v_mul_f32_e32 v100, v109, v101
	v_add_f32_e32 v122, 1.0, v122
	v_add_f32_e32 v123, 1.0, v123
	v_mul_f32_e32 v104, v112, v104
	v_mul_f32_e32 v109, v125, v100
	v_mul_f32_e32 v100, v110, v102
	v_rcp_f32_e32 v122, v122
	v_rcp_f32_e32 v123, v123
	v_mul_f32_e32 v104, v120, v104
	v_mul_f32_e32 v105, v113, v105
	v_mul_f32_e32 v110, v126, v100
	v_mul_f32_e32 v100, v111, v103
	v_mul_f32_e32 v105, v121, v105
	v_mul_f32_e32 v103, v127, v100
	v_cvt_pk_bf16_f32 v100, v104, v105
	v_or_b32_e32 v104, 16, v146
	v_mad_i64_i32 v[104:105], s[16:17], v104, s44, v[116:117]
	v_mul_f32_e32 v106, v114, v106
	v_mul_f32_e32 v107, v115, v107
	v_lshl_add_u64 v[104:105], v[104:105], 0, v[118:119]
	v_mul_f32_e32 v106, v122, v106
	v_mul_f32_e32 v107, v123, v107
	v_cvt_pk_bf16_f32 v101, v106, v107
	v_cvt_pk_bf16_f32 v102, v108, v109
	v_cvt_pk_bf16_f32 v103, v110, v103
	global_store_dwordx4 v[104:105], v[100:103], off sc1
	v_mul_f32_e32 v104, 0xbfb8aa3b, v92
	v_exp_f32_e32 v104, v104
	v_mul_f32_e32 v105, 0xbfb8aa3b, v93
	v_mul_f32_e32 v100, 0xbfb8aa3b, v96
	v_exp_f32_e32 v105, v105
	v_mul_f32_e32 v106, 0xbfb8aa3b, v94
	v_exp_f32_e32 v100, v100
	v_mul_f32_e32 v101, 0xbfb8aa3b, v97
	v_exp_f32_e32 v106, v106
	v_mul_f32_e32 v107, 0xbfb8aa3b, v95
	v_exp_f32_e32 v101, v101
	v_exp_f32_e32 v107, v107
	v_add_f32_e32 v104, 1.0, v104
	v_mul_f32_e32 v102, 0xbfb8aa3b, v98
	v_mul_f32_e32 v103, 0xbfb8aa3b, v99
	v_rcp_f32_e32 v104, v104
	v_add_f32_e32 v105, 1.0, v105
	v_exp_f32_e32 v102, v102
	v_exp_f32_e32 v103, v103
	v_add_f32_e32 v100, 1.0, v100
	v_rcp_f32_e32 v105, v105
	v_add_f32_e32 v106, 1.0, v106
	v_rcp_f32_e32 v100, v100
	v_add_f32_e32 v101, 1.0, v101
	v_rcp_f32_e32 v106, v106
	v_add_f32_e32 v107, 1.0, v107
	v_rcp_f32_e32 v101, v101
	v_rcp_f32_e32 v107, v107
	v_mul_f32_e32 v84, v92, v84
	v_mul_f32_e32 v92, v104, v84
	v_mul_f32_e32 v84, v93, v85
	v_add_f32_e32 v102, 1.0, v102
	v_add_f32_e32 v103, 1.0, v103
	v_mul_f32_e32 v88, v96, v88
	v_mul_f32_e32 v93, v105, v84
	v_mul_f32_e32 v84, v94, v86
	v_rcp_f32_e32 v102, v102
	v_rcp_f32_e32 v103, v103
	v_mul_f32_e32 v88, v100, v88
	v_mul_f32_e32 v89, v97, v89
	v_mul_f32_e32 v94, v106, v84
	v_mul_f32_e32 v84, v95, v87
	v_mul_f32_e32 v89, v101, v89
	v_mul_f32_e32 v87, v107, v84
	v_cvt_pk_bf16_f32 v84, v88, v89
	v_or_b32_e32 v88, 32, v146
	v_mad_i64_i32 v[88:89], s[16:17], v88, s44, v[116:117]
	v_mul_f32_e32 v90, v98, v90
	v_mul_f32_e32 v91, v99, v91
	v_lshl_add_u64 v[88:89], v[88:89], 0, v[118:119]
	v_mul_f32_e32 v90, v102, v90
	v_mul_f32_e32 v91, v103, v91
	v_cvt_pk_bf16_f32 v85, v90, v91
	v_cvt_pk_bf16_f32 v86, v92, v93
	v_cvt_pk_bf16_f32 v87, v94, v87
	global_store_dwordx4 v[88:89], v[84:87], off sc1
	v_mul_f32_e32 v88, 0xbfb8aa3b, v76
	v_exp_f32_e32 v88, v88
	v_mul_f32_e32 v89, 0xbfb8aa3b, v77
; __device__ __forceinline__ unsigned cvt_pk_bf16(float lo, float hi) { unsigned r; asm volatile("v_cvt_pk_bf16_f32 %0, %1, %2" : "=v"(r) : "v"(lo), "v"(hi)); return r; }
;     __device__ __forceinline__ void operator()(const f32x4 (&acc)[2][2][4][2], const Unit& u, int wr, int wc, int fr, int fq) const {
;         const int row0 = u.pm * BM + wr * 64 + fr, col0 = u.pn * HALF + wc * 32 + 8 * fq;
; #pragma unroll
;         for (int ai = 0; ai < 2; ++ai)
; #pragma unroll
;             for (int m = 0; m < 4; ++m) {
;                 float g8[8], u8[8], v[8];
; #pragma unroll
;                 for (int n = 0; n < 2; ++n)
; #pragma unroll
;                     for (int j = 0; j < 4; ++j) { g8[4 * n + j] = acc[ai][0][m][n][j]; u8[4 * n + j] = acc[ai][1][m][n][j]; }
; #pragma unroll
;                 for (int e = 0; e < 8; ++e) v[e] = __builtin_amdgcn_exp2f(-1.4426950408889634f * g8[e]);
; #pragma unroll
;                 for (int e = 0; e < 8; ++e) v[e] = __builtin_amdgcn_rcpf(1.0f + v[e]);
; #pragma unroll
;                 for (int e = 0; e < 8; ++e) v[e] = (g8[e] * u8[e]) * v[e];
;                 u32x4e w; w.x = cvt_pk_bf16(v[0], v[1]); w.y = cvt_pk_bf16(v[2], v[3]); w.z = cvt_pk_bf16(v[4], v[5]); w.w = cvt_pk_bf16(v[6], v[7]);
;                 *(u32x4e*)(H + (size_t)(row0 + ai * HALF + m * 16) * ldc + col0) = w;
;             }
	v_mul_f32_e32 v84, 0xbfb8aa3b, v80
	v_exp_f32_e32 v89, v89
	v_mul_f32_e32 v90, 0xbfb8aa3b, v78
	v_exp_f32_e32 v84, v84
	v_mul_f32_e32 v85, 0xbfb8aa3b, v81
	v_exp_f32_e32 v90, v90
	v_mul_f32_e32 v91, 0xbfb8aa3b, v79
	v_exp_f32_e32 v85, v85
	v_exp_f32_e32 v91, v91
	v_add_f32_e32 v88, 1.0, v88
	v_mul_f32_e32 v86, 0xbfb8aa3b, v82
	v_mul_f32_e32 v87, 0xbfb8aa3b, v83
	v_rcp_f32_e32 v88, v88
	v_add_f32_e32 v89, 1.0, v89
	v_exp_f32_e32 v86, v86
	v_exp_f32_e32 v87, v87
	v_add_f32_e32 v84, 1.0, v84
	v_rcp_f32_e32 v89, v89
	v_add_f32_e32 v90, 1.0, v90
	v_rcp_f32_e32 v84, v84
	v_add_f32_e32 v85, 1.0, v85
	v_rcp_f32_e32 v90, v90
	v_add_f32_e32 v91, 1.0, v91
	v_rcp_f32_e32 v85, v85
	v_rcp_f32_e32 v91, v91
	v_mul_f32_e32 v68, v76, v68
	v_mul_f32_e32 v76, v88, v68
	v_mul_f32_e32 v68, v77, v69
	v_add_f32_e32 v86, 1.0, v86
	v_add_f32_e32 v87, 1.0, v87
	v_mul_f32_e32 v72, v80, v72
	v_mul_f32_e32 v77, v89, v68
	v_mul_f32_e32 v68, v78, v70
	v_rcp_f32_e32 v86, v86
	v_rcp_f32_e32 v87, v87
	v_mul_f32_e32 v72, v84, v72
	v_mul_f32_e32 v73, v81, v73
	v_mul_f32_e32 v78, v90, v68
	v_mul_f32_e32 v68, v79, v71
	v_mul_f32_e32 v73, v85, v73
	v_mul_f32_e32 v71, v91, v68
	v_cvt_pk_bf16_f32 v68, v72, v73
	v_or_b32_e32 v72, 48, v146
	v_mad_i64_i32 v[72:73], s[16:17], v72, s44, v[116:117]
	v_mul_f32_e32 v74, v82, v74
	v_mul_f32_e32 v75, v83, v75
	v_lshl_add_u64 v[72:73], v[72:73], 0, v[118:119]
	v_mul_f32_e32 v74, v86, v74
	v_mul_f32_e32 v75, v87, v75
	v_cvt_pk_bf16_f32 v69, v74, v75
	v_cvt_pk_bf16_f32 v70, v76, v77
	v_cvt_pk_bf16_f32 v71, v78, v71
	global_store_dwordx4 v[72:73], v[68:71], off sc1
	v_mul_f32_e32 v73, 0xbfb8aa3b, v60
	v_exp_f32_e32 v73, v73
	v_mul_f32_e32 v74, 0xbfb8aa3b, v61
	v_mul_f32_e32 v69, 0xbfb8aa3b, v64
	v_mul_f32_e32 v70, 0xbfb8aa3b, v65
	v_exp_f32_e32 v74, v74
	v_mul_f32_e32 v75, 0xbfb8aa3b, v62
	v_exp_f32_e32 v69, v69
	v_exp_f32_e32 v70, v70
	v_exp_f32_e32 v75, v75
	v_mul_f32_e32 v76, 0xbfb8aa3b, v63
	v_exp_f32_e32 v76, v76
	v_mul_f32_e32 v71, 0xbfb8aa3b, v66
	v_mul_f32_e32 v72, 0xbfb8aa3b, v67
	v_add_f32_e32 v73, 1.0, v73
	v_exp_f32_e32 v71, v71
	v_exp_f32_e32 v72, v72
	v_rcp_f32_e32 v73, v73
	v_add_f32_e32 v74, 1.0, v74
	v_add_f32_e32 v69, 1.0, v69
	v_add_f32_e32 v70, 1.0, v70
	v_rcp_f32_e32 v74, v74
	v_add_f32_e32 v75, 1.0, v75
	v_rcp_f32_e32 v69, v69
	v_rcp_f32_e32 v70, v70
	v_rcp_f32_e32 v75, v75
	v_add_f32_e32 v76, 1.0, v76
	v_rcp_f32_e32 v76, v76
	v_mul_f32_e32 v52, v60, v52
	v_add_f32_e32 v71, 1.0, v71
	v_add_f32_e32 v72, 1.0, v72
	v_mul_f32_e32 v60, v73, v52
	v_mul_f32_e32 v52, v61, v53
	v_rcp_f32_e32 v71, v71
	v_rcp_f32_e32 v72, v72
	v_mul_f32_e32 v56, v64, v56
	v_mul_f32_e32 v57, v65, v57
	v_mul_f32_e32 v61, v74, v52
	v_mul_f32_e32 v52, v62, v54
	v_add_u32_e32 v68, 0x80, v146
	v_mul_f32_e32 v56, v69, v56
	v_mul_f32_e32 v57, v70, v57
	v_mul_f32_e32 v62, v75, v52
	v_mul_f32_e32 v52, v63, v55
	v_mul_f32_e32 v55, v76, v52
	v_cvt_pk_bf16_f32 v52, v56, v57
	v_mad_i64_i32 v[56:57], s[16:17], v68, s44, v[116:117]
	v_mul_f32_e32 v58, v66, v58
	v_mul_f32_e32 v59, v67, v59
	v_lshl_add_u64 v[56:57], v[56:57], 0, v[118:119]
	v_mul_f32_e32 v58, v71, v58
	v_mul_f32_e32 v59, v72, v59
	v_cvt_pk_bf16_f32 v53, v58, v59
	v_cvt_pk_bf16_f32 v54, v60, v61
	v_cvt_pk_bf16_f32 v55, v62, v55
	global_store_dwordx4 v[56:57], v[52:55], off sc1
	v_mul_f32_e32 v56, 0xbfb8aa3b, v44
	v_exp_f32_e32 v56, v56
	v_mul_f32_e32 v57, 0xbfb8aa3b, v45
	v_mul_f32_e32 v52, 0xbfb8aa3b, v48
	v_exp_f32_e32 v57, v57
	v_mul_f32_e32 v58, 0xbfb8aa3b, v46
	v_exp_f32_e32 v52, v52
	v_mul_f32_e32 v53, 0xbfb8aa3b, v49
	v_exp_f32_e32 v58, v58
	v_mul_f32_e32 v59, 0xbfb8aa3b, v47
	v_exp_f32_e32 v53, v53
	v_exp_f32_e32 v59, v59
	v_add_f32_e32 v56, 1.0, v56
	v_mul_f32_e32 v54, 0xbfb8aa3b, v50
	v_mul_f32_e32 v55, 0xbfb8aa3b, v51
	v_rcp_f32_e32 v56, v56
	v_add_f32_e32 v57, 1.0, v57
	v_exp_f32_e32 v54, v54
	v_exp_f32_e32 v55, v55
	v_add_f32_e32 v52, 1.0, v52
	v_rcp_f32_e32 v57, v57
	v_add_f32_e32 v58, 1.0, v58
	v_rcp_f32_e32 v52, v52
	v_add_f32_e32 v53, 1.0, v53
	v_rcp_f32_e32 v58, v58
	v_add_f32_e32 v59, 1.0, v59
	v_rcp_f32_e32 v53, v53
	v_rcp_f32_e32 v59, v59
	v_mul_f32_e32 v36, v44, v36
	v_mul_f32_e32 v44, v56, v36
	v_mul_f32_e32 v36, v45, v37
	v_add_f32_e32 v54, 1.0, v54
	v_add_f32_e32 v55, 1.0, v55
; __device__ __forceinline__ unsigned cvt_pk_bf16(float lo, float hi) { unsigned r; asm volatile("v_cvt_pk_bf16_f32 %0, %1, %2" : "=v"(r) : "v"(lo), "v"(hi)); return r; }
; #define PG8_BAR __builtin_amdgcn_s_barrier()
; template <class Epi, class Sched, bool ALIGN_EPI = false, bool SP2 = false>
; __device__ __forceinline__ void gemm_phase(PG8_LAS unsigned char* lds, const Gemm g, const Sched& S, const Epi& E) {
;     ...
;         if constexpr (ALIGN_EPI) { if (wr == 1) PG8_BAR; }
;     __device__ __forceinline__ void operator()(const f32x4 (&acc)[2][2][4][2], const Unit& u, int wr, int wc, int fr, int fq) const {
;     ...
;         for (int ai = 0; ai < 2; ++ai)
; #pragma unroll
;             for (int m = 0; m < 4; ++m) {
;                 float g8[8], u8[8], v[8];
; #pragma unroll
;                 for (int n = 0; n < 2; ++n)
; #pragma unroll
;                     for (int j = 0; j < 4; ++j) { g8[4 * n + j] = acc[ai][0][m][n][j]; u8[4 * n + j] = acc[ai][1][m][n][j]; }
; #pragma unroll
;                 for (int e = 0; e < 8; ++e) v[e] = __builtin_amdgcn_exp2f(-1.4426950408889634f * g8[e]);
; #pragma unroll
;                 for (int e = 0; e < 8; ++e) v[e] = __builtin_amdgcn_rcpf(1.0f + v[e]);
; #pragma unroll
;                 for (int e = 0; e < 8; ++e) v[e] = (g8[e] * u8[e]) * v[e];
;                 u32x4e w; w.x = cvt_pk_bf16(v[0], v[1]); w.y = cvt_pk_bf16(v[2], v[3]); w.z = cvt_pk_bf16(v[4], v[5]); w.w = cvt_pk_bf16(v[6], v[7]);
;                 *(u32x4e*)(H + (size_t)(row0 + ai * HALF + m * 16) * ldc + col0) = w;
;             }
	v_mul_f32_e32 v40, v48, v40
	v_mul_f32_e32 v45, v57, v36
	v_mul_f32_e32 v36, v46, v38
	v_rcp_f32_e32 v54, v54
	v_rcp_f32_e32 v55, v55
	v_mul_f32_e32 v40, v52, v40
	v_mul_f32_e32 v41, v49, v41
	v_mul_f32_e32 v46, v58, v36
	v_mul_f32_e32 v36, v47, v39
	v_mul_f32_e32 v41, v53, v41
	v_mul_f32_e32 v39, v59, v36
	v_cvt_pk_bf16_f32 v36, v40, v41
	v_add_u32_e32 v40, 0x90, v146
	v_mad_i64_i32 v[40:41], s[16:17], v40, s44, v[116:117]
	v_mul_f32_e32 v42, v50, v42
	v_mul_f32_e32 v43, v51, v43
	v_lshl_add_u64 v[40:41], v[40:41], 0, v[118:119]
	v_mul_f32_e32 v42, v54, v42
	v_mul_f32_e32 v43, v55, v43
	v_cvt_pk_bf16_f32 v37, v42, v43
	v_cvt_pk_bf16_f32 v38, v44, v45
	v_cvt_pk_bf16_f32 v39, v46, v39
	global_store_dwordx4 v[40:41], v[36:39], off sc1
	v_mul_f32_e32 v40, 0xbfb8aa3b, v28
	v_exp_f32_e32 v40, v40
	v_mul_f32_e32 v41, 0xbfb8aa3b, v29
	v_mul_f32_e32 v36, 0xbfb8aa3b, v32
	v_exp_f32_e32 v41, v41
	v_mul_f32_e32 v42, 0xbfb8aa3b, v30
	v_exp_f32_e32 v36, v36
	v_mul_f32_e32 v37, 0xbfb8aa3b, v33
	v_exp_f32_e32 v42, v42
	v_mul_f32_e32 v43, 0xbfb8aa3b, v31
	v_exp_f32_e32 v37, v37
	v_exp_f32_e32 v43, v43
	v_add_f32_e32 v40, 1.0, v40
	v_mul_f32_e32 v38, 0xbfb8aa3b, v34
	v_mul_f32_e32 v39, 0xbfb8aa3b, v35
	v_rcp_f32_e32 v40, v40
	v_add_f32_e32 v41, 1.0, v41
	v_exp_f32_e32 v38, v38
	v_exp_f32_e32 v39, v39
	v_add_f32_e32 v36, 1.0, v36
	v_rcp_f32_e32 v41, v41
	v_add_f32_e32 v42, 1.0, v42
	v_rcp_f32_e32 v36, v36
	v_add_f32_e32 v37, 1.0, v37
	v_rcp_f32_e32 v42, v42
	v_add_f32_e32 v43, 1.0, v43
	v_rcp_f32_e32 v37, v37
	v_rcp_f32_e32 v43, v43
	v_mul_f32_e32 v20, v28, v20
	v_mul_f32_e32 v28, v40, v20
	v_mul_f32_e32 v20, v29, v21
	v_add_f32_e32 v38, 1.0, v38
	v_add_f32_e32 v39, 1.0, v39
	v_mul_f32_e32 v24, v32, v24
	v_mul_f32_e32 v29, v41, v20
	v_mul_f32_e32 v20, v30, v22
	v_rcp_f32_e32 v38, v38
	v_rcp_f32_e32 v39, v39
	v_mul_f32_e32 v24, v36, v24
	v_mul_f32_e32 v25, v33, v25
	v_mul_f32_e32 v30, v42, v20
	v_mul_f32_e32 v20, v31, v23
	v_mul_f32_e32 v25, v37, v25
	v_mul_f32_e32 v23, v43, v20
	v_cvt_pk_bf16_f32 v20, v24, v25
	v_add_u32_e32 v24, 0xa0, v146
	v_mad_i64_i32 v[24:25], s[16:17], v24, s44, v[116:117]
	v_mul_f32_e32 v26, v34, v26
	v_mul_f32_e32 v27, v35, v27
	v_lshl_add_u64 v[24:25], v[24:25], 0, v[118:119]
	v_mul_f32_e32 v26, v38, v26
	v_mul_f32_e32 v27, v39, v27
	v_cvt_pk_bf16_f32 v21, v26, v27
	v_cvt_pk_bf16_f32 v22, v28, v29
	v_cvt_pk_bf16_f32 v23, v30, v23
	global_store_dwordx4 v[24:25], v[20:23], off sc1
	v_mul_f32_e32 v24, 0xbfb8aa3b, v12
	v_exp_f32_e32 v24, v24
	v_mul_f32_e32 v25, 0xbfb8aa3b, v13
	v_mul_f32_e32 v20, 0xbfb8aa3b, v16
	v_exp_f32_e32 v25, v25
	v_mul_f32_e32 v26, 0xbfb8aa3b, v14
	v_exp_f32_e32 v20, v20
	v_mul_f32_e32 v21, 0xbfb8aa3b, v17
	v_exp_f32_e32 v26, v26
	v_mul_f32_e32 v27, 0xbfb8aa3b, v15
	v_exp_f32_e32 v21, v21
	v_exp_f32_e32 v27, v27
	v_add_f32_e32 v24, 1.0, v24
	v_mul_f32_e32 v22, 0xbfb8aa3b, v18
	v_mul_f32_e32 v23, 0xbfb8aa3b, v19
	v_rcp_f32_e32 v24, v24
	v_add_f32_e32 v25, 1.0, v25
	v_exp_f32_e32 v22, v22
	v_exp_f32_e32 v23, v23
	v_add_f32_e32 v20, 1.0, v20
	v_rcp_f32_e32 v25, v25
	v_add_f32_e32 v26, 1.0, v26
	v_rcp_f32_e32 v20, v20
	v_add_f32_e32 v21, 1.0, v21
	v_rcp_f32_e32 v26, v26
	v_add_f32_e32 v27, 1.0, v27
	v_rcp_f32_e32 v21, v21
	v_rcp_f32_e32 v27, v27
	v_mul_f32_e32 v4, v12, v4
	v_mul_f32_e32 v12, v24, v4
	v_mul_f32_e32 v4, v13, v5
	v_add_f32_e32 v22, 1.0, v22
	v_add_f32_e32 v23, 1.0, v23
	v_mul_f32_e32 v8, v16, v8
	v_mul_f32_e32 v13, v25, v4
	v_mul_f32_e32 v4, v14, v6
	v_rcp_f32_e32 v22, v22
	v_rcp_f32_e32 v23, v23
	v_mul_f32_e32 v8, v20, v8
	v_mul_f32_e32 v9, v17, v9
	v_mul_f32_e32 v14, v26, v4
	v_mul_f32_e32 v4, v15, v7
	v_mul_f32_e32 v9, v21, v9
	v_mul_f32_e32 v7, v27, v4
	v_cvt_pk_bf16_f32 v4, v8, v9
	v_add_u32_e32 v8, 0xb0, v146
	v_mad_i64_i32 v[8:9], s[16:17], v8, s44, v[116:117]
	v_mul_f32_e32 v10, v18, v10
	v_mul_f32_e32 v11, v19, v11
	v_lshl_add_u64 v[8:9], v[8:9], 0, v[118:119]
	s_andn2_b64 vcc, exec, s[0:1]
	s_mov_b64 s[0:1], -1
	v_mul_f32_e32 v10, v22, v10
	v_mul_f32_e32 v11, v23, v11
	v_cvt_pk_bf16_f32 v5, v10, v11
	v_cvt_pk_bf16_f32 v6, v12, v13
	v_cvt_pk_bf16_f32 v7, v14, v7
	global_store_dwordx4 v[8:9], v[4:7], off sc1
	s_cbranch_vccnz .LBB0_879
	s_andn2_b64 vcc, exec, s[4:5]
	s_cbranch_vccnz .LBB0_878
	s_barrier
	s_branch .LBB0_878
